# v17 + GEMM K-loops: one static s_setprio 1 for waves 0-3 per tile, per-segment priority flips deleted
# speedup vs baseline: 1.0040x; 1.0001x over previous
.LBB0_31:
	s_ashr_i32 s19, s18, 31
	s_lshl_b64 s[4:5], s[18:19], 21
	s_add_u32 s20, s34, s4
	s_addc_u32 s21, s35, s5
	s_and_b64 s[4:5], s[6:7], exec
	s_cselect_b32 s1, s21, s27
	s_cselect_b32 s2, s20, s26
	s_ashr_i32 s17, s16, 31
	s_lshl_b64 s[4:5], s[16:17], 21
	s_add_u32 s22, s36, s4
	s_addc_u32 s23, s37, s5
	s_and_b64 s[4:5], s[6:7], exec
	s_cselect_b32 s4, s23, s29
	s_cselect_b32 s5, s22, s28
	s_add_u32 s26, s26, 0x100080
	s_addc_u32 s27, s27, 0
	s_add_u32 s17, s28, 0x100
	v_mov_b32_e32 v4, 0
	s_addc_u32 s19, s29, 0
	s_mov_b32 s25, -2
	v_mov_b32_e32 v5, v4
	v_mov_b32_e32 v6, v4
	v_mov_b32_e32 v7, v4
	v_mov_b32_e32 v8, v4
	v_mov_b32_e32 v9, v4
	v_mov_b32_e32 v10, v4
	v_mov_b32_e32 v11, v4
	v_mov_b32_e32 v20, v4
	v_mov_b32_e32 v21, v4
	v_mov_b32_e32 v22, v4
	v_mov_b32_e32 v23, v4
	v_mov_b32_e32 v24, v4
	v_mov_b32_e32 v25, v4
	v_mov_b32_e32 v26, v4
	v_mov_b32_e32 v27, v4
	v_mov_b32_e32 v36, v4
	v_mov_b32_e32 v37, v4
	v_mov_b32_e32 v38, v4
	v_mov_b32_e32 v39, v4
	v_mov_b32_e32 v40, v4
	v_mov_b32_e32 v41, v4
	v_mov_b32_e32 v42, v4
	v_mov_b32_e32 v43, v4
	v_mov_b32_e32 v44, v4
	v_mov_b32_e32 v45, v4
	v_mov_b32_e32 v46, v4
	v_mov_b32_e32 v47, v4
	v_mov_b32_e32 v48, v4
	v_mov_b32_e32 v49, v4
	v_mov_b32_e32 v50, v4
	v_mov_b32_e32 v51, v4
	v_mov_b32_e32 v12, v4
	v_mov_b32_e32 v13, v4
	v_mov_b32_e32 v14, v4
	v_mov_b32_e32 v15, v4
	v_mov_b32_e32 v16, v4
	v_mov_b32_e32 v17, v4
	v_mov_b32_e32 v18, v4
	v_mov_b32_e32 v19, v4
	v_mov_b32_e32 v28, v4
	v_mov_b32_e32 v29, v4
	v_mov_b32_e32 v30, v4
	v_mov_b32_e32 v31, v4
	v_mov_b32_e32 v32, v4
	v_mov_b32_e32 v33, v4
	v_mov_b32_e32 v34, v4
	v_mov_b32_e32 v35, v4
	v_mov_b32_e32 v52, v4
	v_mov_b32_e32 v53, v4
	v_mov_b32_e32 v54, v4
	v_mov_b32_e32 v55, v4
	v_mov_b32_e32 v56, v4
	v_mov_b32_e32 v57, v4
	v_mov_b32_e32 v58, v4
	v_mov_b32_e32 v59, v4
	v_mov_b32_e32 v60, v4
	v_mov_b32_e32 v61, v4
	v_mov_b32_e32 v62, v4
	v_mov_b32_e32 v63, v4
	v_mov_b32_e32 v64, v4
	v_mov_b32_e32 v65, v4
	v_mov_b32_e32 v66, v4
	v_mov_b32_e32 v67, v4
	v_mov_b32_e32 v84, v4
	v_mov_b32_e32 v85, v4
	v_mov_b32_e32 v86, v4
	v_mov_b32_e32 v87, v4
	v_mov_b32_e32 v88, v4
	v_mov_b32_e32 v89, v4
	v_mov_b32_e32 v90, v4
	v_mov_b32_e32 v91, v4
	v_mov_b32_e32 v92, v4
	v_mov_b32_e32 v93, v4
	v_mov_b32_e32 v94, v4
	v_mov_b32_e32 v95, v4
	v_mov_b32_e32 v96, v4
	v_mov_b32_e32 v97, v4
	v_mov_b32_e32 v98, v4
	v_mov_b32_e32 v99, v4
	v_mov_b32_e32 v116, v4
	v_mov_b32_e32 v117, v4
	v_mov_b32_e32 v118, v4
	v_mov_b32_e32 v119, v4
	v_mov_b32_e32 v120, v4
	v_mov_b32_e32 v121, v4
	v_mov_b32_e32 v122, v4
	v_mov_b32_e32 v123, v4
	v_mov_b32_e32 v124, v4
	v_mov_b32_e32 v125, v4
	v_mov_b32_e32 v126, v4
	v_mov_b32_e32 v127, v4
	v_mov_b32_e32 v128, v4
	v_mov_b32_e32 v129, v4
	v_mov_b32_e32 v130, v4
	v_mov_b32_e32 v131, v4
	v_mov_b32_e32 v100, v4
	v_mov_b32_e32 v101, v4
	v_mov_b32_e32 v102, v4
	v_mov_b32_e32 v103, v4
	v_mov_b32_e32 v104, v4
	v_mov_b32_e32 v105, v4
	v_mov_b32_e32 v106, v4
	v_mov_b32_e32 v107, v4
	v_mov_b32_e32 v108, v4
	v_mov_b32_e32 v109, v4
	v_mov_b32_e32 v110, v4
	v_mov_b32_e32 v111, v4
	v_mov_b32_e32 v112, v4
	v_mov_b32_e32 v113, v4
	v_mov_b32_e32 v114, v4
	v_mov_b32_e32 v115, v4
	v_mov_b32_e32 v132, v4
	v_mov_b32_e32 v133, v4
	v_mov_b32_e32 v134, v4
	v_mov_b32_e32 v135, v4
	v_mov_b32_e32 v136, v4
	v_mov_b32_e32 v137, v4
	v_mov_b32_e32 v138, v4
	v_mov_b32_e32 v139, v4
	v_mov_b32_e32 v140, v4
	v_mov_b32_e32 v141, v4
	v_mov_b32_e32 v142, v4
	v_mov_b32_e32 v143, v4
	v_mov_b32_e32 v144, v4
	v_mov_b32_e32 v145, v4
	v_mov_b32_e32 v146, v4
	v_mov_b32_e32 v147, v4
	s_waitcnt vmcnt(0)
	v_readfirstlane_b32 s101, v186
	s_nop 3
	s_lshr_b32 s101, s101, 8
	s_cmp_eq_u32 s101, 0
	s_cbranch_scc0 .Lprio_0
	s_setprio 1

.LBB0_75:
	s_mov_b32 s18, s2
	s_ashr_i32 s19, s2, 31
	s_mov_b32 s14, s5
	s_mov_b32 s16, s4
	s_lshl_b64 s[4:5], s[18:19], 21
	s_add_u32 s2, s38, s4
	s_mov_b32 s6, s15
	s_addc_u32 s4, s39, s5
	s_ashr_i32 s15, s14, 31
	s_lshl_b64 s[24:25], s[14:15], 1
	s_add_u32 s22, s2, s24
	s_addc_u32 s23, s4, s25
	s_and_b64 s[4:5], s[20:21], exec
	s_cselect_b32 s2, s23, s31
	s_cselect_b32 s4, s22, s30
	s_ashr_i32 s17, s16, 31
	s_lshl_b64 s[36:37], s[16:17], 21
	s_add_u32 s5, s40, s36
	s_mov_b32 s97, s7
	s_addc_u32 s7, s41, s37
	s_add_u32 s24, s5, s24
	s_addc_u32 s25, s7, s25
	s_and_b64 s[36:37], s[20:21], exec
	s_cselect_b32 s5, s25, s35
	s_cselect_b32 s7, s24, s34
	s_add_i32 s15, s1, -2
	s_add_u32 s30, s30, 0x100080
	s_addc_u32 s31, s31, 0
	s_add_u32 s17, s34, 0x100
	v_mov_b32_e32 v4, 0
	s_addc_u32 s19, s35, 0
	s_mov_b32 s27, 0
	v_mov_b32_e32 v5, v4
	v_mov_b32_e32 v6, v4
	v_mov_b32_e32 v7, v4
	v_mov_b32_e32 v8, v4
	v_mov_b32_e32 v9, v4
	v_mov_b32_e32 v10, v4
	v_mov_b32_e32 v11, v4
	v_mov_b32_e32 v20, v4
	v_mov_b32_e32 v21, v4
	v_mov_b32_e32 v22, v4
	v_mov_b32_e32 v23, v4
	v_mov_b32_e32 v24, v4
	v_mov_b32_e32 v25, v4
	v_mov_b32_e32 v26, v4
	v_mov_b32_e32 v27, v4
	v_mov_b32_e32 v36, v4
	v_mov_b32_e32 v37, v4
	v_mov_b32_e32 v38, v4
	v_mov_b32_e32 v39, v4
	v_mov_b32_e32 v40, v4
	v_mov_b32_e32 v41, v4
	v_mov_b32_e32 v42, v4
	v_mov_b32_e32 v43, v4
	v_mov_b32_e32 v44, v4
	v_mov_b32_e32 v45, v4
	v_mov_b32_e32 v46, v4
	v_mov_b32_e32 v47, v4
	v_mov_b32_e32 v48, v4
	v_mov_b32_e32 v49, v4
	v_mov_b32_e32 v50, v4
	v_mov_b32_e32 v51, v4
	v_mov_b32_e32 v12, v4
	v_mov_b32_e32 v13, v4
	v_mov_b32_e32 v14, v4
	v_mov_b32_e32 v15, v4
	v_mov_b32_e32 v16, v4
	v_mov_b32_e32 v17, v4
	v_mov_b32_e32 v18, v4
	v_mov_b32_e32 v19, v4
	v_mov_b32_e32 v28, v4
	v_mov_b32_e32 v29, v4
	v_mov_b32_e32 v30, v4
	v_mov_b32_e32 v31, v4
	v_mov_b32_e32 v32, v4
	v_mov_b32_e32 v33, v4
	v_mov_b32_e32 v34, v4
	v_mov_b32_e32 v35, v4
	v_mov_b32_e32 v52, v4
	v_mov_b32_e32 v53, v4
	v_mov_b32_e32 v54, v4
	v_mov_b32_e32 v55, v4
	v_mov_b32_e32 v56, v4
	v_mov_b32_e32 v57, v4
	v_mov_b32_e32 v58, v4
	v_mov_b32_e32 v59, v4
	v_mov_b32_e32 v60, v4
	v_mov_b32_e32 v61, v4
	v_mov_b32_e32 v62, v4
	v_mov_b32_e32 v63, v4
	v_mov_b32_e32 v64, v4
	v_mov_b32_e32 v65, v4
	v_mov_b32_e32 v66, v4
	v_mov_b32_e32 v67, v4
	s_waitcnt vmcnt(0)
	v_mov_b32_e32 v68, v4
	v_mov_b32_e32 v69, v4
	v_mov_b32_e32 v70, v4
	v_mov_b32_e32 v71, v4
	v_mov_b32_e32 v72, v4
	v_mov_b32_e32 v73, v4
	v_mov_b32_e32 v74, v4
	v_mov_b32_e32 v75, v4
	v_mov_b32_e32 v80, v4
	v_mov_b32_e32 v81, v4
	v_mov_b32_e32 v82, v4
	v_mov_b32_e32 v83, v4
	v_mov_b32_e32 v88, v4
	v_mov_b32_e32 v89, v4
	v_mov_b32_e32 v90, v4
	v_mov_b32_e32 v91, v4
	v_mov_b32_e32 v116, v4
	v_mov_b32_e32 v117, v4
	v_mov_b32_e32 v118, v4
	v_mov_b32_e32 v119, v4
	v_mov_b32_e32 v120, v4
	v_mov_b32_e32 v121, v4
	v_mov_b32_e32 v122, v4
	v_mov_b32_e32 v123, v4
	v_mov_b32_e32 v124, v4
	v_mov_b32_e32 v125, v4
	v_mov_b32_e32 v126, v4
	v_mov_b32_e32 v127, v4
	v_mov_b32_e32 v128, v4
	v_mov_b32_e32 v129, v4
	v_mov_b32_e32 v130, v4
	v_mov_b32_e32 v131, v4
	v_mov_b32_e32 v92, v4
	v_mov_b32_e32 v93, v4
	v_mov_b32_e32 v94, v4
	v_mov_b32_e32 v95, v4
	v_mov_b32_e32 v100, v4
	v_mov_b32_e32 v101, v4
	v_mov_b32_e32 v102, v4
	v_mov_b32_e32 v103, v4
	v_mov_b32_e32 v104, v4
	v_mov_b32_e32 v105, v4
	v_mov_b32_e32 v106, v4
	v_mov_b32_e32 v107, v4
	v_mov_b32_e32 v108, v4
	v_mov_b32_e32 v109, v4
	v_mov_b32_e32 v110, v4
	v_mov_b32_e32 v111, v4
	v_mov_b32_e32 v132, v4
	v_mov_b32_e32 v133, v4
	v_mov_b32_e32 v134, v4
	v_mov_b32_e32 v135, v4
	v_mov_b32_e32 v136, v4
	v_mov_b32_e32 v137, v4
	v_mov_b32_e32 v138, v4
	v_mov_b32_e32 v139, v4
	v_mov_b32_e32 v140, v4
	v_mov_b32_e32 v141, v4
	v_mov_b32_e32 v142, v4
	v_mov_b32_e32 v143, v4
	v_mov_b32_e32 v144, v4
	v_mov_b32_e32 v145, v4
	v_mov_b32_e32 v146, v4
	v_mov_b32_e32 v147, v4
	v_readfirstlane_b32 s101, v186
	s_nop 3
	s_lshr_b32 s101, s101, 8
	s_cmp_eq_u32 s101, 0
	s_cbranch_scc0 .Lprio_1
	s_setprio 1

.LBB0_104:
	s_ashr_i32 s17, s16, 31
	s_lshl_b64 s[4:5], s[16:17], 19
	s_add_u32 s18, s0, s4
	s_addc_u32 s19, s2, s5
	s_and_b64 s[4:5], s[6:7], exec
	s_cselect_b32 s4, s19, s25
	s_cselect_b32 s5, s18, s24
	s_ashr_i32 s15, s14, 31
	s_lshl_b64 s[20:21], s[14:15], 19
	s_add_u32 s20, s30, s20
	s_addc_u32 s21, s31, s21
	s_and_b64 s[28:29], s[6:7], exec
	s_cselect_b32 s15, s21, s27
	s_cselect_b32 s17, s20, s26
	s_add_u32 s24, s24, 0x40080
	s_addc_u32 s25, s25, 0
	s_add_u32 s50, s26, 0x100
	s_addc_u32 s51, s27, 0
	s_mov_b32 s54, -2
	v_readfirstlane_b32 s101, v186
	s_nop 3
	s_lshr_b32 s101, s101, 8
	s_cmp_eq_u32 s101, 0
	s_cbranch_scc0 .Lprio_2
	s_setprio 1

.LBB0_254:
	s_ashr_i32 s21, s20, 31
	s_lshl_b64 s[4:5], s[20:21], 19
	s_add_u32 s22, s36, s4
	s_addc_u32 s23, s37, s5
	s_and_b64 s[4:5], s[6:7], exec
	s_cselect_b32 s1, s23, s29
	s_cselect_b32 s2, s22, s28
	s_ashr_i32 s19, s18, 31
	s_lshl_b64 s[4:5], s[18:19], 19
	s_add_u32 s24, s38, s4
	s_addc_u32 s25, s39, s5
	s_and_b64 s[4:5], s[6:7], exec
	s_cselect_b32 s4, s25, s31
	s_cselect_b32 s5, s24, s30
	s_add_u32 s28, s28, 0x40080
	s_addc_u32 s29, s29, 0
	s_add_u32 s19, s30, 0x100
	v_mov_b32_e32 v4, 0
	s_addc_u32 s21, s31, 0
	s_mov_b32 s27, -2
	v_mov_b32_e32 v5, v4
	v_mov_b32_e32 v6, v4
	v_mov_b32_e32 v7, v4
	v_mov_b32_e32 v8, v4
	v_mov_b32_e32 v9, v4
	v_mov_b32_e32 v10, v4
	v_mov_b32_e32 v11, v4
	v_mov_b32_e32 v20, v4
	v_mov_b32_e32 v21, v4
	v_mov_b32_e32 v22, v4
	v_mov_b32_e32 v23, v4
	v_mov_b32_e32 v24, v4
	v_mov_b32_e32 v25, v4
	v_mov_b32_e32 v26, v4
	v_mov_b32_e32 v27, v4
	v_mov_b32_e32 v36, v4
	v_mov_b32_e32 v37, v4
	v_mov_b32_e32 v38, v4
	v_mov_b32_e32 v39, v4
	v_mov_b32_e32 v40, v4
	v_mov_b32_e32 v41, v4
	v_mov_b32_e32 v42, v4
	v_mov_b32_e32 v43, v4
	v_mov_b32_e32 v44, v4
	v_mov_b32_e32 v45, v4
	v_mov_b32_e32 v46, v4
	v_mov_b32_e32 v47, v4
	v_mov_b32_e32 v48, v4
	v_mov_b32_e32 v49, v4
	v_mov_b32_e32 v50, v4
	v_mov_b32_e32 v51, v4
	v_mov_b32_e32 v12, v4
	v_mov_b32_e32 v13, v4
	v_mov_b32_e32 v14, v4
	v_mov_b32_e32 v15, v4
	v_mov_b32_e32 v16, v4
	v_mov_b32_e32 v17, v4
	v_mov_b32_e32 v18, v4
	v_mov_b32_e32 v19, v4
	v_mov_b32_e32 v28, v4
	v_mov_b32_e32 v29, v4
	v_mov_b32_e32 v30, v4
	v_mov_b32_e32 v31, v4
	v_mov_b32_e32 v32, v4
	v_mov_b32_e32 v33, v4
	v_mov_b32_e32 v34, v4
	v_mov_b32_e32 v35, v4
	v_mov_b32_e32 v52, v4
	v_mov_b32_e32 v53, v4
	v_mov_b32_e32 v54, v4
	v_mov_b32_e32 v55, v4
	v_mov_b32_e32 v56, v4
	v_mov_b32_e32 v57, v4
	v_mov_b32_e32 v58, v4
	v_mov_b32_e32 v59, v4
	v_mov_b32_e32 v60, v4
	v_mov_b32_e32 v61, v4
	v_mov_b32_e32 v62, v4
	v_mov_b32_e32 v63, v4
	v_mov_b32_e32 v64, v4
	v_mov_b32_e32 v65, v4
	v_mov_b32_e32 v66, v4
	v_mov_b32_e32 v67, v4
	v_mov_b32_e32 v84, v4
	v_mov_b32_e32 v85, v4
	v_mov_b32_e32 v86, v4
	v_mov_b32_e32 v87, v4
	v_mov_b32_e32 v88, v4
	v_mov_b32_e32 v89, v4
	v_mov_b32_e32 v90, v4
	v_mov_b32_e32 v91, v4
	v_mov_b32_e32 v92, v4
	v_mov_b32_e32 v93, v4
	v_mov_b32_e32 v94, v4
	v_mov_b32_e32 v95, v4
	v_mov_b32_e32 v96, v4
	v_mov_b32_e32 v97, v4
	v_mov_b32_e32 v98, v4
	v_mov_b32_e32 v99, v4
	v_mov_b32_e32 v116, v4
	v_mov_b32_e32 v117, v4
	v_mov_b32_e32 v118, v4
	v_mov_b32_e32 v119, v4
	v_mov_b32_e32 v120, v4
	v_mov_b32_e32 v121, v4
	v_mov_b32_e32 v122, v4
	v_mov_b32_e32 v123, v4
	v_mov_b32_e32 v124, v4
	v_mov_b32_e32 v125, v4
	v_mov_b32_e32 v126, v4
	v_mov_b32_e32 v127, v4
	v_mov_b32_e32 v128, v4
	v_mov_b32_e32 v129, v4
	v_mov_b32_e32 v130, v4
	v_mov_b32_e32 v131, v4
	v_mov_b32_e32 v100, v4
	v_mov_b32_e32 v101, v4
	v_mov_b32_e32 v102, v4
	v_mov_b32_e32 v103, v4
	v_mov_b32_e32 v104, v4
	v_mov_b32_e32 v105, v4
	v_mov_b32_e32 v106, v4
	v_mov_b32_e32 v107, v4
	v_mov_b32_e32 v108, v4
	v_mov_b32_e32 v109, v4
	v_mov_b32_e32 v110, v4
	v_mov_b32_e32 v111, v4
	v_mov_b32_e32 v112, v4
	v_mov_b32_e32 v113, v4
	v_mov_b32_e32 v114, v4
	v_mov_b32_e32 v115, v4
	v_mov_b32_e32 v132, v4
	v_mov_b32_e32 v133, v4
	v_mov_b32_e32 v134, v4
	v_mov_b32_e32 v135, v4
	v_mov_b32_e32 v136, v4
	v_mov_b32_e32 v137, v4
	v_mov_b32_e32 v138, v4
	v_mov_b32_e32 v139, v4
	v_mov_b32_e32 v140, v4
	v_mov_b32_e32 v141, v4
	v_mov_b32_e32 v142, v4
	v_mov_b32_e32 v143, v4
	v_mov_b32_e32 v144, v4
	v_mov_b32_e32 v145, v4
	v_mov_b32_e32 v146, v4
	v_mov_b32_e32 v147, v4
	s_waitcnt vmcnt(0)
	v_readfirstlane_b32 s101, v186
	s_nop 3
	s_lshr_b32 s101, s101, 8
	s_cmp_eq_u32 s101, 0
	s_cbranch_scc0 .Lprio_3
	s_setprio 1

.LBB0_299:
	s_mov_b32 s20, s2
	s_ashr_i32 s21, s2, 31
	s_mov_b32 s16, s5
	s_mov_b32 s18, s4
	s_lshl_b64 s[4:5], s[20:21], 19
	s_add_u32 s2, s40, s4
	s_mov_b32 s55, s17
	s_addc_u32 s4, s41, s5
	s_ashr_i32 s17, s16, 31
	s_lshl_b64 s[26:27], s[16:17], 1
	s_add_u32 s24, s2, s26
	s_addc_u32 s25, s4, s27
	s_and_b64 s[4:5], s[22:23], exec
	s_mov_b32 s54, s19
	s_cselect_b32 s2, s25, s35
	s_cselect_b32 s4, s24, s34
	s_ashr_i32 s19, s18, 31
	s_lshl_b64 s[38:39], s[18:19], 19
	s_add_u32 s5, s42, s38
	s_addc_u32 s17, s43, s39
	s_add_u32 s26, s5, s26
	s_addc_u32 s27, s17, s27
	s_and_b64 s[38:39], s[22:23], exec
	s_cselect_b32 s5, s27, s37
	s_cselect_b32 s17, s26, s36
	s_add_i32 s19, s1, -2
	s_add_u32 s34, s34, 0x40080
	s_addc_u32 s35, s35, 0
	s_add_u32 s21, s36, 0x100
	v_mov_b32_e32 v4, 0
	s_addc_u32 s29, s37, 0
	s_mov_b32 s31, 0
	v_mov_b32_e32 v5, v4
	v_mov_b32_e32 v6, v4
	v_mov_b32_e32 v7, v4
	v_mov_b32_e32 v8, v4
	v_mov_b32_e32 v9, v4
	v_mov_b32_e32 v10, v4
	v_mov_b32_e32 v11, v4
	v_mov_b32_e32 v16, v4
	v_mov_b32_e32 v17, v4
	v_mov_b32_e32 v18, v4
	v_mov_b32_e32 v19, v4
	v_mov_b32_e32 v20, v4
	v_mov_b32_e32 v21, v4
	v_mov_b32_e32 v22, v4
	v_mov_b32_e32 v23, v4
	v_mov_b32_e32 v36, v4
	v_mov_b32_e32 v37, v4
	v_mov_b32_e32 v38, v4
	v_mov_b32_e32 v39, v4
	v_mov_b32_e32 v40, v4
	v_mov_b32_e32 v41, v4
	v_mov_b32_e32 v42, v4
	v_mov_b32_e32 v43, v4
	v_mov_b32_e32 v44, v4
	v_mov_b32_e32 v45, v4
	v_mov_b32_e32 v46, v4
	v_mov_b32_e32 v47, v4
	v_mov_b32_e32 v48, v4
	v_mov_b32_e32 v49, v4
	v_mov_b32_e32 v50, v4
	v_mov_b32_e32 v51, v4
	v_mov_b32_e32 v12, v4
	v_mov_b32_e32 v13, v4
	v_mov_b32_e32 v14, v4
	v_mov_b32_e32 v15, v4
	v_mov_b32_e32 v24, v4
	v_mov_b32_e32 v25, v4
	v_mov_b32_e32 v26, v4
	v_mov_b32_e32 v27, v4
	v_mov_b32_e32 v28, v4
	v_mov_b32_e32 v29, v4
	v_mov_b32_e32 v30, v4
	v_mov_b32_e32 v31, v4
	v_mov_b32_e32 v32, v4
	v_mov_b32_e32 v33, v4
	v_mov_b32_e32 v34, v4
	v_mov_b32_e32 v35, v4
	v_mov_b32_e32 v52, v4
	v_mov_b32_e32 v53, v4
	v_mov_b32_e32 v54, v4
	v_mov_b32_e32 v55, v4
	v_mov_b32_e32 v56, v4
	v_mov_b32_e32 v57, v4
	v_mov_b32_e32 v58, v4
	v_mov_b32_e32 v59, v4
	v_mov_b32_e32 v60, v4
	v_mov_b32_e32 v61, v4
	v_mov_b32_e32 v62, v4
	v_mov_b32_e32 v63, v4
	v_mov_b32_e32 v64, v4
	v_mov_b32_e32 v65, v4
	v_mov_b32_e32 v66, v4
	v_mov_b32_e32 v67, v4
	v_mov_b32_e32 v68, v4
	v_mov_b32_e32 v69, v4
	v_mov_b32_e32 v70, v4
	v_mov_b32_e32 v71, v4
	v_mov_b32_e32 v72, v4
	v_mov_b32_e32 v73, v4
	v_mov_b32_e32 v74, v4
	v_mov_b32_e32 v75, v4
	v_mov_b32_e32 v76, v4
	v_mov_b32_e32 v77, v4
	v_mov_b32_e32 v78, v4
	v_mov_b32_e32 v79, v4
	v_mov_b32_e32 v80, v4
	v_mov_b32_e32 v81, v4
	v_mov_b32_e32 v82, v4
	v_mov_b32_e32 v83, v4
	v_mov_b32_e32 v112, v4
	v_mov_b32_e32 v113, v4
	v_mov_b32_e32 v114, v4
	v_mov_b32_e32 v115, v4
	v_mov_b32_e32 v116, v4
	v_mov_b32_e32 v117, v4
	v_mov_b32_e32 v118, v4
	v_mov_b32_e32 v119, v4
	v_mov_b32_e32 v120, v4
	v_mov_b32_e32 v121, v4
	v_mov_b32_e32 v122, v4
	v_mov_b32_e32 v123, v4
	v_mov_b32_e32 v124, v4
	v_mov_b32_e32 v125, v4
	v_mov_b32_e32 v126, v4
	v_mov_b32_e32 v127, v4
	v_mov_b32_e32 v84, v4
	v_mov_b32_e32 v85, v4
	v_mov_b32_e32 v86, v4
	v_mov_b32_e32 v87, v4
	v_mov_b32_e32 v88, v4
	v_mov_b32_e32 v89, v4
	v_mov_b32_e32 v90, v4
	v_mov_b32_e32 v91, v4
	v_mov_b32_e32 v92, v4
	v_mov_b32_e32 v93, v4
	v_mov_b32_e32 v94, v4
	v_mov_b32_e32 v95, v4
	v_mov_b32_e32 v96, v4
	v_mov_b32_e32 v97, v4
	v_mov_b32_e32 v98, v4
	v_mov_b32_e32 v99, v4
	v_mov_b32_e32 v132, v4
	v_mov_b32_e32 v133, v4
	v_mov_b32_e32 v134, v4
	v_mov_b32_e32 v135, v4
	v_mov_b32_e32 v136, v4
	v_mov_b32_e32 v137, v4
	v_mov_b32_e32 v138, v4
	v_mov_b32_e32 v139, v4
	v_mov_b32_e32 v140, v4
	v_mov_b32_e32 v141, v4
	v_mov_b32_e32 v142, v4
	v_mov_b32_e32 v143, v4
	v_mov_b32_e32 v144, v4
	v_mov_b32_e32 v145, v4
	v_mov_b32_e32 v146, v4
	v_mov_b32_e32 v147, v4
	s_waitcnt vmcnt(0)
	v_readfirstlane_b32 s101, v186
	s_nop 3
	s_lshr_b32 s101, s101, 8
	s_cmp_eq_u32 s101, 0
	s_cbranch_scc0 .Lprio_4
	s_setprio 1

.LBB0_670:
	s_ashr_i32 s21, s20, 31
	s_lshl_b64 s[0:1], s[20:21], 19
	s_add_u32 s22, s8, s0
	s_addc_u32 s23, s9, s1
	s_and_b64 s[0:1], s[6:7], exec
	s_cselect_b32 s0, s23, s31
	s_cselect_b32 s1, s22, s30
	s_ashr_i32 s19, s18, 31
	s_lshl_b64 s[4:5], s[18:19], 19
	s_add_u32 s24, s40, s4
	s_addc_u32 s25, s41, s5
	s_and_b64 s[4:5], s[6:7], exec
	s_cselect_b32 s2, s25, s35
	s_cselect_b32 s4, s24, s34
	s_add_u32 s30, s30, 0x40080
	s_addc_u32 s31, s31, 0
	s_add_u32 s5, s34, 0x100
	s_addc_u32 s19, s35, 0
	s_mov_b32 s21, -2
	v_readfirstlane_b32 s101, v186
	s_nop 3
	s_lshr_b32 s101, s101, 8
	s_cmp_eq_u32 s101, 0
	s_cbranch_scc0 .Lprio_5
	s_setprio 1
